# attention LDS-DMA piece setup: s_cselect_b64 + SGPR-pair operand instead of two s_cselect_b32 and two v_mov (2 VALU + 1 SALU less per piece)
# speedup vs baseline: 1.0070x; 1.0008x over previous
; __device__ __forceinline__ void attn_unit(LAS unsigned char* lds, int b, int h, int qb, const bf16_t* Q, const bf16_t* KF, const bf16_t* VT,
;                                           const float* gout, bf16_t* MIXED, int wave, int lane) {
;     ...
;     ATT_ISSUE(0, 0);
;     __syncthreads();
;     f32x16 oacc[4];
; #pragma unroll
;     for (int db = 0; db < 4; ++db)
; #pragma unroll
;         for (int i = 0; i < 16; ++i) oacc[db][i] = 0.f;
;     float m_run = -INFINITY, l_run = 0.f;
;     for (int kt = 0; kt < nkt; ++kt) {
;         if (kt + 1 < nkt) ATT_ISSUE(kt + 1, (kt + 1) & 1);
.LBB0_447:
	s_add_i32 m0, s81, s0
	s_and_b64 vcc, s[72:73], exec
	s_cselect_b64 s[56:57], s[62:63], s[52:53]
	v_lshl_add_u64 v[64:65], v[96:97], 1, s[56:57]
	global_load_lds_dwordx4 v[64:65], off
	s_and_b64 vcc, exec, s[6:7]
	s_cbranch_vccnz .LBB0_442
.LBB0_448:
	s_add_i32 m0, s81, s44
	s_and_b64 vcc, s[82:83], exec
	s_cselect_b64 s[56:57], s[62:63], s[52:53]
	v_lshl_add_u64 v[64:65], v[98:99], 1, s[56:57]
	global_load_lds_dwordx4 v[64:65], off
	s_and_b64 vcc, exec, s[8:9]
	s_cbranch_vccnz .LBB0_443
.LBB0_449:
	s_add_i32 m0, s81, s45
	s_and_b64 vcc, s[92:93], exec
	s_cselect_b64 s[56:57], s[62:63], s[52:53]
	v_lshl_add_u64 v[64:65], v[100:101], 1, s[56:57]
	global_load_lds_dwordx4 v[64:65], off
	s_and_b64 vcc, exec, s[10:11]
	s_cbranch_vccnz .LBB0_444
.LBB0_450:
	s_add_i32 m0, s81, s1
	s_and_b64 vcc, s[66:67], exec
	s_cselect_b64 s[56:57], s[62:63], s[52:53]
	v_lshl_add_u64 v[64:65], v[102:103], 1, s[56:57]
	global_load_lds_dwordx4 v[64:65], off
	s_and_b64 vcc, exec, s[12:13]
	s_cbranch_vccnz .LBB0_445
.LBB0_451:
	s_add_i32 m0, s81, s64
	s_and_b64 vcc, s[90:91], exec
	s_cselect_b64 s[56:57], s[62:63], s[52:53]
	v_lshl_add_u64 v[64:65], v[104:105], 1, s[56:57]
	global_load_lds_dwordx4 v[64:65], off
	s_and_b64 vcc, exec, s[14:15]
	s_cbranch_vccnz .LBB0_446
.LBB0_452:
	s_add_i32 m0, s81, s65
	s_and_b64 vcc, s[78:79], exec
	s_cselect_b64 s[56:57], s[62:63], s[52:53]
	v_lshl_add_u64 v[64:65], v[206:207], 1, s[56:57]
	global_load_lds_dwordx4 v[64:65], off
	s_cmp_gt_i32 s80, s70
	s_cbranch_scc1 .LBB0_458

; __device__ __forceinline__ void attn_unit(LAS unsigned char* lds, int b, int h, int qb, const bf16_t* Q, const bf16_t* KF, const bf16_t* VT,
;                                           const float* gout, bf16_t* MIXED, int wave, int lane) {
;     ...
;     ATT_ISSUE(0, 0);
;     __syncthreads();
;     f32x16 oacc[4];
; #pragma unroll
;     for (int db = 0; db < 4; ++db)
; #pragma unroll
;         for (int i = 0; i < 16; ++i) oacc[db][i] = 0.f;
;     float m_run = -INFINITY, l_run = 0.f;
;     for (int kt = 0; kt < nkt; ++kt) {
;         if (kt + 1 < nkt) ATT_ISSUE(kt + 1, (kt + 1) & 1);
.LBB0_500:
	s_add_i32 m0, s23, s0
	s_and_b64 s[26:27], s[72:73], exec
	s_cselect_b64 s[26:27], s[18:19], s[16:17]
	v_lshl_add_u64 v[64:65], v[96:97], 1, s[26:27]
	global_load_lds_dwordx4 v[64:65], off
	s_and_b64 vcc, exec, s[6:7]
	s_cbranch_vccnz .LBB0_495
.LBB0_501:
	s_add_i32 m0, s23, s44
	s_and_b64 s[26:27], s[82:83], exec
	s_cselect_b64 s[26:27], s[18:19], s[16:17]
	v_lshl_add_u64 v[64:65], v[98:99], 1, s[26:27]
	global_load_lds_dwordx4 v[64:65], off
	s_and_b64 vcc, exec, s[8:9]
	s_cbranch_vccnz .LBB0_496
.LBB0_502:
	s_add_i32 m0, s23, s45
	s_and_b64 s[26:27], s[92:93], exec
	s_cselect_b64 s[26:27], s[18:19], s[16:17]
	v_lshl_add_u64 v[64:65], v[100:101], 1, s[26:27]
	global_load_lds_dwordx4 v[64:65], off
	s_and_b64 vcc, exec, s[10:11]
	s_cbranch_vccnz .LBB0_497
.LBB0_503:
	s_add_i32 m0, s23, s1
	s_and_b64 s[26:27], s[66:67], exec
	s_cselect_b64 s[26:27], s[18:19], s[16:17]
	v_lshl_add_u64 v[64:65], v[102:103], 1, s[26:27]
	global_load_lds_dwordx4 v[64:65], off
	s_and_b64 vcc, exec, s[12:13]
	s_cbranch_vccnz .LBB0_498
.LBB0_504:
	s_add_i32 m0, s23, s64
	s_and_b64 s[26:27], s[90:91], exec
	s_cselect_b64 s[26:27], s[18:19], s[16:17]
	v_lshl_add_u64 v[64:65], v[104:105], 1, s[26:27]
	global_load_lds_dwordx4 v[64:65], off
	s_and_b64 vcc, exec, s[14:15]
	s_cbranch_vccnz .LBB0_499
.LBB0_505:
	s_add_i32 m0, s23, s65
	s_and_b64 s[26:27], s[78:79], exec
	s_cselect_b64 s[26:27], s[18:19], s[16:17]
	v_lshl_add_u64 v[64:65], v[206:207], 1, s[26:27]
	global_load_lds_dwordx4 v[64:65], off
	s_cmp_gt_i32 s22, s21
	s_cbranch_scc1 .LBB0_511
